# FFN1 pre-norm: all 8 rows of a wave loaded up front into spare register banks (was one row in flight)
# speedup vs baseline: 1.0001x; 1.0001x over previous
.LBB0_80:
	s_ashr_i32 s5, s10, 8
	v_mad_i64_i32 v[0:1], s[8:9], s5, v216, v[20:21]
	v_mad_i64_i32 v[12:13], s[8:9], s5, v216, v[18:19]
	global_load_dwordx4 v[30:33], v[0:1], off
	global_load_dwordx4 v[34:37], v[0:1], off offset:1024
	global_load_dwordx4 v[38:41], v[0:1], off offset:2048
	global_load_dwordx4 v[42:45], v[0:1], off offset:3072
	global_load_dwordx4 v[46:49], v[16:17], off
	global_load_dwordx4 v[50:53], v[16:17], off offset:1024
	global_load_dwordx4 v[54:57], v[16:17], off offset:2048
	global_load_dwordx4 v[58:61], v[16:17], off offset:3072
	s_nop 0
	global_load_dwordx4 v[0:3], v[12:13], off
	global_load_dwordx4 v[4:7], v[12:13], off offset:1024
	global_load_dwordx4 v[8:11], v[12:13], off offset:2048
	s_nop 0
	global_load_dwordx4 v[12:15], v[12:13], off offset:3072
	s_ashr_i32 s5, s4, 31
	s_lshl_b64 s[8:9], s[4:5], 11
	s_lshl_b64 s[12:13], s[4:5], 12
	v_lshl_add_u64 v[26:27], v[22:23], 0, s[8:9]
	v_lshl_add_u64 v[28:29], v[24:25], 0, s[12:13]
	s_mov_b64 s[8:9], 0
	s_waitcnt vmcnt(11)
	v_pk_add_f32 v[32:33], v[32:33], 1.0 op_sel_hi:[1,0]
	v_pk_add_f32 v[62:63], v[30:31], 1.0 op_sel_hi:[1,0]
	s_waitcnt vmcnt(10)
	v_pk_add_f32 v[36:37], v[36:37], 1.0 op_sel_hi:[1,0]
	v_pk_add_f32 v[64:65], v[34:35], 1.0 op_sel_hi:[1,0]
	s_waitcnt vmcnt(9)
	v_pk_add_f32 v[40:41], v[40:41], 1.0 op_sel_hi:[1,0]
	v_pk_add_f32 v[66:67], v[38:39], 1.0 op_sel_hi:[1,0]
	s_waitcnt vmcnt(8)
	v_pk_add_f32 v[44:45], v[44:45], 1.0 op_sel_hi:[1,0]
	v_pk_add_f32 v[68:69], v[42:43], 1.0 op_sel_hi:[1,0]
	s_waitcnt vmcnt(7)
	v_pk_mul_f32 v[30:31], v[48:49], v[32:33]
	v_pk_mul_f32 v[32:33], v[46:47], v[62:63]
	s_waitcnt vmcnt(6)
	v_pk_mul_f32 v[34:35], v[52:53], v[36:37]
	v_pk_mul_f32 v[36:37], v[50:51], v[64:65]
	s_waitcnt vmcnt(5)
	v_pk_mul_f32 v[38:39], v[56:57], v[40:41]
	v_pk_mul_f32 v[40:41], v[54:55], v[66:67]
	s_waitcnt vmcnt(4)
	v_pk_mul_f32 v[42:43], v[60:61], v[44:45]
	v_pk_mul_f32 v[44:45], v[58:59], v[68:69]
	global_load_dwordx4 v[84:87], v[28:29], off offset:-3072
	global_load_dwordx4 v[88:91], v[28:29], off offset:-2048
	global_load_dwordx4 v[92:95], v[28:29], off offset:-1024
	global_load_dwordx4 v[96:99], v[28:29], off
	v_lshl_add_u64 v[28:29], v[28:29], 0, s[66:67]
	global_load_dwordx4 v[100:103], v[28:29], off offset:-3072
	global_load_dwordx4 v[104:107], v[28:29], off offset:-2048
	global_load_dwordx4 v[108:111], v[28:29], off offset:-1024
	global_load_dwordx4 v[112:115], v[28:29], off
	v_lshl_add_u64 v[28:29], v[28:29], 0, s[66:67]
	global_load_dwordx4 v[116:119], v[28:29], off offset:-3072
	global_load_dwordx4 v[120:123], v[28:29], off offset:-2048
	global_load_dwordx4 v[124:127], v[28:29], off offset:-1024
	global_load_dwordx4 v[128:131], v[28:29], off
	v_lshl_add_u64 v[28:29], v[28:29], 0, s[66:67]
	global_load_dwordx4 v[132:135], v[28:29], off offset:-3072
	global_load_dwordx4 v[136:139], v[28:29], off offset:-2048
	global_load_dwordx4 v[140:143], v[28:29], off offset:-1024
	global_load_dwordx4 v[144:147], v[28:29], off
	v_lshl_add_u64 v[28:29], v[28:29], 0, s[66:67]
	global_load_dwordx4 v[180:183], v[28:29], off offset:-3072
	global_load_dwordx4 v[184:187], v[28:29], off offset:-2048
	global_load_dwordx4 v[188:191], v[28:29], off offset:-1024
	global_load_dwordx4 v[192:195], v[28:29], off
	v_lshl_add_u64 v[28:29], v[28:29], 0, s[66:67]
	global_load_dwordx4 v[196:199], v[28:29], off offset:-3072
	global_load_dwordx4 v[200:203], v[28:29], off offset:-2048
	global_load_dwordx4 v[204:207], v[28:29], off offset:-1024
	global_load_dwordx4 v[208:211], v[28:29], off
	v_lshl_add_u64 v[28:29], v[28:29], 0, s[66:67]
	global_load_dwordx4 v[226:229], v[28:29], off offset:-3072
	global_load_dwordx4 v[230:233], v[28:29], off offset:-2048
	global_load_dwordx4 v[234:237], v[28:29], off offset:-1024
	global_load_dwordx4 v[238:241], v[28:29], off
	v_lshl_add_u64 v[28:29], v[28:29], 0, s[66:67]
	s_waitcnt vmcnt(24)
	s_nop 1
	v_mov_b32_e32 v46, v84
	v_mov_b32_e32 v47, v85
	v_mov_b32_e32 v48, v86
	v_mov_b32_e32 v49, v87
	v_mov_b32_e32 v50, v88
	v_mov_b32_e32 v51, v89
	v_mov_b32_e32 v52, v90
	v_mov_b32_e32 v53, v91
	v_mov_b32_e32 v54, v92
	v_mov_b32_e32 v55, v93
	v_mov_b32_e32 v56, v94
	v_mov_b32_e32 v57, v95
	v_mov_b32_e32 v58, v96
	v_mov_b32_e32 v59, v97
	v_mov_b32_e32 v60, v98
	v_mov_b32_e32 v61, v99
	global_load_dwordx4 v[84:87], v[28:29], off offset:-3072
	global_load_dwordx4 v[88:91], v[28:29], off offset:-2048
	global_load_dwordx4 v[92:95], v[28:29], off offset:-1024
	global_load_dwordx4 v[96:99], v[28:29], off
	v_lshl_add_u64 v[28:29], v[28:29], 0, s[66:67]
	v_lshl_add_u64 v[62:63], v[26:27], 0, s[8:9]
	s_add_u32 s8, s8, 0x800
	s_addc_u32 s9, s9, 0
	v_add_co_u32_e32 v62, vcc, s78, v62
	s_nop 0
	s_nop 0
	v_addc_co_u32_e32 v63, vcc, 0, v63, vcc
	v_pk_mul_f32 v[64:65], v[48:49], v[48:49]
	v_pk_mul_f32 v[66:67], v[46:47], v[46:47]
	v_pk_mul_f32 v[68:69], v[52:53], v[52:53]
	v_pk_mul_f32 v[70:71], v[50:51], v[50:51]
	v_pk_mov_b32 v[76:77], v[66:67], v[64:65] op_sel:[1,0]
	v_mov_b32_e32 v67, v65
	v_pk_mov_b32 v[64:65], v[70:71], v[68:69] op_sel:[1,0]
	v_mov_b32_e32 v71, v69
	v_mul_f32_e32 v75, v58, v58
	v_mul_f32_e32 v72, v55, v55
	v_mul_f32_e32 v74, v57, v57
	v_pk_add_f32 v[66:67], v[76:77], v[66:67]
	v_pk_add_f32 v[64:65], v[64:65], v[70:71]
	v_mul_f32_e32 v78, v59, v59
	v_mul_f32_e32 v79, v60, v60
	v_mul_f32_e32 v80, v61, v61
	v_pk_fma_f32 v[68:69], v[54:55], v[54:55], v[72:73] op_sel_hi:[1,1,0]
	v_pk_fma_f32 v[72:73], v[56:57], v[56:57], v[74:75] op_sel_hi:[1,1,0]
	v_pk_add_f32 v[66:67], v[66:67], v[66:67] op_sel:[0,1] op_sel_hi:[1,0]
	v_pk_add_f32 v[64:65], v[64:65], v[64:65] op_sel:[0,1] op_sel_hi:[1,0]
	v_mov_b32_e32 v69, v79
	v_mov_b32_e32 v73, v80
	v_mov_b32_e32 v67, v75
	v_mov_b32_e32 v65, v78
	v_pk_add_f32 v[68:69], v[68:69], v[72:73]
	v_pk_add_f32 v[64:65], v[66:67], v[64:65]
	s_nop 0
	v_pk_add_f32 v[64:65], v[64:65], v[68:69]
	s_nop 0
	v_add_f32_e32 v64, v64, v65
	s_nop 1
	v_add_f32_dpp v64, v64, v64 quad_perm:[1,0,3,2] row_mask:0xf bank_mask:0xf bound_ctrl:1
	s_nop 1
	v_add_f32_dpp v64, v64, v64 quad_perm:[2,3,0,1] row_mask:0xf bank_mask:0xf bound_ctrl:1
	s_nop 1
	v_add_f32_dpp v64, v64, v64 row_half_mirror row_mask:0xf bank_mask:0xf bound_ctrl:1
	s_nop 1
	v_add_f32_dpp v64, v64, v64 row_mirror row_mask:0xf bank_mask:0xf bound_ctrl:1
	s_nop 0
	v_readlane_b32 s5, v64, 16
	v_readlane_b32 s11, v64, 48
	v_readlane_b32 s12, v64, 0
	v_readlane_b32 s13, v64, 32
	v_mov_b32_e32 v64, s5
	v_mov_b32_e32 v65, s11
	v_pk_add_f32 v[64:65], s[12:13], v[64:65]
	s_nop 0
	v_add_f32_e32 v64, v64, v65
	v_fmamk_f32 v64, v64, 0x3a800000, v212
	v_rsq_f32_e32 v64, v64
	s_nop 0
	v_pk_mul_f32 v[46:47], v[46:47], v[64:65] op_sel_hi:[1,0]
	v_pk_mul_f32 v[48:49], v[48:49], v[64:65] op_sel_hi:[1,0]
	v_pk_mul_f32 v[50:51], v[50:51], v[64:65] op_sel_hi:[1,0]
	v_pk_mul_f32 v[52:53], v[52:53], v[64:65] op_sel_hi:[1,0]
	v_pk_mul_f32 v[54:55], v[54:55], v[64:65] op_sel_hi:[1,0]
	v_pk_mul_f32 v[56:57], v[56:57], v[64:65] op_sel_hi:[1,0]
	v_pk_mul_f32 v[58:59], v[58:59], v[64:65] op_sel_hi:[1,0]
	v_pk_mul_f32 v[60:61], v[60:61], v[64:65] op_sel_hi:[1,0]
	v_pk_fma_f32 v[48:49], v[30:31], v[48:49], v[2:3]
	v_pk_fma_f32 v[46:47], v[32:33], v[46:47], v[0:1]
	v_pk_fma_f32 v[52:53], v[34:35], v[52:53], v[6:7]
	v_pk_fma_f32 v[50:51], v[36:37], v[50:51], v[4:5]
	v_pk_fma_f32 v[56:57], v[38:39], v[56:57], v[10:11]
	v_pk_fma_f32 v[54:55], v[40:41], v[54:55], v[8:9]
	v_pk_fma_f32 v[60:61], v[42:43], v[60:61], v[14:15]
	v_pk_fma_f32 v[58:59], v[44:45], v[58:59], v[12:13]
	v_cvt_pk_bf16_f32 v46, v46, v47
	v_cvt_pk_bf16_f32 v47, v48, v49
	v_cvt_pk_bf16_f32 v48, v50, v51
	v_cvt_pk_bf16_f32 v49, v52, v53
	v_cvt_pk_bf16_f32 v50, v54, v55
	v_cvt_pk_bf16_f32 v51, v56, v57
	v_cvt_pk_bf16_f32 v52, v58, v59
	v_cvt_pk_bf16_f32 v53, v60, v61
	global_store_dwordx2 v[62:63], v[46:47], off
	global_store_dwordx2 v[62:63], v[48:49], off offset:512
	global_store_dwordx2 v[62:63], v[50:51], off offset:1024
	global_store_dwordx2 v[62:63], v[52:53], off offset:1536
	s_waitcnt vmcnt(28)
	s_nop 1
	v_mov_b32_e32 v46, v100
	v_mov_b32_e32 v47, v101
	v_mov_b32_e32 v48, v102
	v_mov_b32_e32 v49, v103
	v_mov_b32_e32 v50, v104
	v_mov_b32_e32 v51, v105
	v_mov_b32_e32 v52, v106
	v_mov_b32_e32 v53, v107
	v_mov_b32_e32 v54, v108
	v_mov_b32_e32 v55, v109
	v_mov_b32_e32 v56, v110
	v_mov_b32_e32 v57, v111
	v_mov_b32_e32 v58, v112
	v_mov_b32_e32 v59, v113
	v_mov_b32_e32 v60, v114
	v_mov_b32_e32 v61, v115
	v_lshl_add_u64 v[62:63], v[26:27], 0, s[8:9]
	s_add_u32 s8, s8, 0x800
	s_addc_u32 s9, s9, 0
	v_add_co_u32_e32 v62, vcc, s78, v62
	s_nop 0
	s_nop 0
	v_addc_co_u32_e32 v63, vcc, 0, v63, vcc
	v_pk_mul_f32 v[64:65], v[48:49], v[48:49]
	v_pk_mul_f32 v[66:67], v[46:47], v[46:47]
	v_pk_mul_f32 v[68:69], v[52:53], v[52:53]
	v_pk_mul_f32 v[70:71], v[50:51], v[50:51]
	v_pk_mov_b32 v[76:77], v[66:67], v[64:65] op_sel:[1,0]
	v_mov_b32_e32 v67, v65
	v_pk_mov_b32 v[64:65], v[70:71], v[68:69] op_sel:[1,0]
	v_mov_b32_e32 v71, v69
	v_mul_f32_e32 v75, v58, v58
	v_mul_f32_e32 v72, v55, v55
	v_mul_f32_e32 v74, v57, v57
	v_pk_add_f32 v[66:67], v[76:77], v[66:67]
	v_pk_add_f32 v[64:65], v[64:65], v[70:71]
	v_mul_f32_e32 v78, v59, v59
	v_mul_f32_e32 v79, v60, v60
	v_mul_f32_e32 v80, v61, v61
	v_pk_fma_f32 v[68:69], v[54:55], v[54:55], v[72:73] op_sel_hi:[1,1,0]
	v_pk_fma_f32 v[72:73], v[56:57], v[56:57], v[74:75] op_sel_hi:[1,1,0]
	v_pk_add_f32 v[66:67], v[66:67], v[66:67] op_sel:[0,1] op_sel_hi:[1,0]
	v_pk_add_f32 v[64:65], v[64:65], v[64:65] op_sel:[0,1] op_sel_hi:[1,0]
	v_mov_b32_e32 v69, v79
	v_mov_b32_e32 v73, v80
	v_mov_b32_e32 v67, v75
	v_mov_b32_e32 v65, v78
	v_pk_add_f32 v[68:69], v[68:69], v[72:73]
	v_pk_add_f32 v[64:65], v[66:67], v[64:65]
	s_nop 0
	v_pk_add_f32 v[64:65], v[64:65], v[68:69]
	s_nop 0
	v_add_f32_e32 v64, v64, v65
	s_nop 1
	v_add_f32_dpp v64, v64, v64 quad_perm:[1,0,3,2] row_mask:0xf bank_mask:0xf bound_ctrl:1
	s_nop 1
	v_add_f32_dpp v64, v64, v64 quad_perm:[2,3,0,1] row_mask:0xf bank_mask:0xf bound_ctrl:1
	s_nop 1
	v_add_f32_dpp v64, v64, v64 row_half_mirror row_mask:0xf bank_mask:0xf bound_ctrl:1
	s_nop 1
	v_add_f32_dpp v64, v64, v64 row_mirror row_mask:0xf bank_mask:0xf bound_ctrl:1
	s_nop 0
	v_readlane_b32 s5, v64, 16
	v_readlane_b32 s11, v64, 48
	v_readlane_b32 s12, v64, 0
	v_readlane_b32 s13, v64, 32
	v_mov_b32_e32 v64, s5
	v_mov_b32_e32 v65, s11
	v_pk_add_f32 v[64:65], s[12:13], v[64:65]
	s_nop 0
	v_add_f32_e32 v64, v64, v65
	v_fmamk_f32 v64, v64, 0x3a800000, v212
	v_rsq_f32_e32 v64, v64
	s_nop 0
	v_pk_mul_f32 v[46:47], v[46:47], v[64:65] op_sel_hi:[1,0]
	v_pk_mul_f32 v[48:49], v[48:49], v[64:65] op_sel_hi:[1,0]
	v_pk_mul_f32 v[50:51], v[50:51], v[64:65] op_sel_hi:[1,0]
	v_pk_mul_f32 v[52:53], v[52:53], v[64:65] op_sel_hi:[1,0]
	v_pk_mul_f32 v[54:55], v[54:55], v[64:65] op_sel_hi:[1,0]
	v_pk_mul_f32 v[56:57], v[56:57], v[64:65] op_sel_hi:[1,0]
	v_pk_mul_f32 v[58:59], v[58:59], v[64:65] op_sel_hi:[1,0]
	v_pk_mul_f32 v[60:61], v[60:61], v[64:65] op_sel_hi:[1,0]
	v_pk_fma_f32 v[48:49], v[30:31], v[48:49], v[2:3]
	v_pk_fma_f32 v[46:47], v[32:33], v[46:47], v[0:1]
	v_pk_fma_f32 v[52:53], v[34:35], v[52:53], v[6:7]
	v_pk_fma_f32 v[50:51], v[36:37], v[50:51], v[4:5]
	v_pk_fma_f32 v[56:57], v[38:39], v[56:57], v[10:11]
	v_pk_fma_f32 v[54:55], v[40:41], v[54:55], v[8:9]
	v_pk_fma_f32 v[60:61], v[42:43], v[60:61], v[14:15]
	v_pk_fma_f32 v[58:59], v[44:45], v[58:59], v[12:13]
	v_cvt_pk_bf16_f32 v46, v46, v47
	v_cvt_pk_bf16_f32 v47, v48, v49
	v_cvt_pk_bf16_f32 v48, v50, v51
	v_cvt_pk_bf16_f32 v49, v52, v53
	v_cvt_pk_bf16_f32 v50, v54, v55
	v_cvt_pk_bf16_f32 v51, v56, v57
	v_cvt_pk_bf16_f32 v52, v58, v59
	v_cvt_pk_bf16_f32 v53, v60, v61
	global_store_dwordx2 v[62:63], v[46:47], off
	global_store_dwordx2 v[62:63], v[48:49], off offset:512
	global_store_dwordx2 v[62:63], v[50:51], off offset:1024
	global_store_dwordx2 v[62:63], v[52:53], off offset:1536
	s_waitcnt vmcnt(28)
	s_nop 1
	v_mov_b32_e32 v46, v116
	v_mov_b32_e32 v47, v117
	v_mov_b32_e32 v48, v118
	v_mov_b32_e32 v49, v119
	v_mov_b32_e32 v50, v120
	v_mov_b32_e32 v51, v121
	v_mov_b32_e32 v52, v122
	v_mov_b32_e32 v53, v123
	v_mov_b32_e32 v54, v124
	v_mov_b32_e32 v55, v125
	v_mov_b32_e32 v56, v126
	v_mov_b32_e32 v57, v127
	v_mov_b32_e32 v58, v128
	v_mov_b32_e32 v59, v129
	v_mov_b32_e32 v60, v130
	v_mov_b32_e32 v61, v131
	v_lshl_add_u64 v[62:63], v[26:27], 0, s[8:9]
	s_add_u32 s8, s8, 0x800
	s_addc_u32 s9, s9, 0
	v_add_co_u32_e32 v62, vcc, s78, v62
	s_nop 0
	s_nop 0
	v_addc_co_u32_e32 v63, vcc, 0, v63, vcc
	v_pk_mul_f32 v[64:65], v[48:49], v[48:49]
	v_pk_mul_f32 v[66:67], v[46:47], v[46:47]
	v_pk_mul_f32 v[68:69], v[52:53], v[52:53]
	v_pk_mul_f32 v[70:71], v[50:51], v[50:51]
	v_pk_mov_b32 v[76:77], v[66:67], v[64:65] op_sel:[1,0]
	v_mov_b32_e32 v67, v65
	v_pk_mov_b32 v[64:65], v[70:71], v[68:69] op_sel:[1,0]
	v_mov_b32_e32 v71, v69
	v_mul_f32_e32 v75, v58, v58
	v_mul_f32_e32 v72, v55, v55
	v_mul_f32_e32 v74, v57, v57
	v_pk_add_f32 v[66:67], v[76:77], v[66:67]
	v_pk_add_f32 v[64:65], v[64:65], v[70:71]
	v_mul_f32_e32 v78, v59, v59
	v_mul_f32_e32 v79, v60, v60
	v_mul_f32_e32 v80, v61, v61
	v_pk_fma_f32 v[68:69], v[54:55], v[54:55], v[72:73] op_sel_hi:[1,1,0]
	v_pk_fma_f32 v[72:73], v[56:57], v[56:57], v[74:75] op_sel_hi:[1,1,0]
	v_pk_add_f32 v[66:67], v[66:67], v[66:67] op_sel:[0,1] op_sel_hi:[1,0]
	v_pk_add_f32 v[64:65], v[64:65], v[64:65] op_sel:[0,1] op_sel_hi:[1,0]
	v_mov_b32_e32 v69, v79
	v_mov_b32_e32 v73, v80
	v_mov_b32_e32 v67, v75
	v_mov_b32_e32 v65, v78
	v_pk_add_f32 v[68:69], v[68:69], v[72:73]
	v_pk_add_f32 v[64:65], v[66:67], v[64:65]
	s_nop 0
	v_pk_add_f32 v[64:65], v[64:65], v[68:69]
	s_nop 0
	v_add_f32_e32 v64, v64, v65
	s_nop 1
	v_add_f32_dpp v64, v64, v64 quad_perm:[1,0,3,2] row_mask:0xf bank_mask:0xf bound_ctrl:1
	s_nop 1
	v_add_f32_dpp v64, v64, v64 quad_perm:[2,3,0,1] row_mask:0xf bank_mask:0xf bound_ctrl:1
	s_nop 1
	v_add_f32_dpp v64, v64, v64 row_half_mirror row_mask:0xf bank_mask:0xf bound_ctrl:1
	s_nop 1
	v_add_f32_dpp v64, v64, v64 row_mirror row_mask:0xf bank_mask:0xf bound_ctrl:1
	s_nop 0
	v_readlane_b32 s5, v64, 16
	v_readlane_b32 s11, v64, 48
	v_readlane_b32 s12, v64, 0
	v_readlane_b32 s13, v64, 32
	v_mov_b32_e32 v64, s5
	v_mov_b32_e32 v65, s11
	v_pk_add_f32 v[64:65], s[12:13], v[64:65]
	s_nop 0
	v_add_f32_e32 v64, v64, v65
	v_fmamk_f32 v64, v64, 0x3a800000, v212
	v_rsq_f32_e32 v64, v64
	s_nop 0
	v_pk_mul_f32 v[46:47], v[46:47], v[64:65] op_sel_hi:[1,0]
	v_pk_mul_f32 v[48:49], v[48:49], v[64:65] op_sel_hi:[1,0]
	v_pk_mul_f32 v[50:51], v[50:51], v[64:65] op_sel_hi:[1,0]
	v_pk_mul_f32 v[52:53], v[52:53], v[64:65] op_sel_hi:[1,0]
	v_pk_mul_f32 v[54:55], v[54:55], v[64:65] op_sel_hi:[1,0]
	v_pk_mul_f32 v[56:57], v[56:57], v[64:65] op_sel_hi:[1,0]
	v_pk_mul_f32 v[58:59], v[58:59], v[64:65] op_sel_hi:[1,0]
	v_pk_mul_f32 v[60:61], v[60:61], v[64:65] op_sel_hi:[1,0]
	v_pk_fma_f32 v[48:49], v[30:31], v[48:49], v[2:3]
	v_pk_fma_f32 v[46:47], v[32:33], v[46:47], v[0:1]
	v_pk_fma_f32 v[52:53], v[34:35], v[52:53], v[6:7]
	v_pk_fma_f32 v[50:51], v[36:37], v[50:51], v[4:5]
	v_pk_fma_f32 v[56:57], v[38:39], v[56:57], v[10:11]
	v_pk_fma_f32 v[54:55], v[40:41], v[54:55], v[8:9]
	v_pk_fma_f32 v[60:61], v[42:43], v[60:61], v[14:15]
	v_pk_fma_f32 v[58:59], v[44:45], v[58:59], v[12:13]
	v_cvt_pk_bf16_f32 v46, v46, v47
	v_cvt_pk_bf16_f32 v47, v48, v49
	v_cvt_pk_bf16_f32 v48, v50, v51
	v_cvt_pk_bf16_f32 v49, v52, v53
	v_cvt_pk_bf16_f32 v50, v54, v55
	v_cvt_pk_bf16_f32 v51, v56, v57
	v_cvt_pk_bf16_f32 v52, v58, v59
	v_cvt_pk_bf16_f32 v53, v60, v61
	global_store_dwordx2 v[62:63], v[46:47], off
	global_store_dwordx2 v[62:63], v[48:49], off offset:512
	global_store_dwordx2 v[62:63], v[50:51], off offset:1024
	global_store_dwordx2 v[62:63], v[52:53], off offset:1536
	s_waitcnt vmcnt(28)
	s_nop 1
	v_mov_b32_e32 v46, v132
	v_mov_b32_e32 v47, v133
	v_mov_b32_e32 v48, v134
	v_mov_b32_e32 v49, v135
	v_mov_b32_e32 v50, v136
	v_mov_b32_e32 v51, v137
	v_mov_b32_e32 v52, v138
	v_mov_b32_e32 v53, v139
	v_mov_b32_e32 v54, v140
	v_mov_b32_e32 v55, v141
	v_mov_b32_e32 v56, v142
	v_mov_b32_e32 v57, v143
	v_mov_b32_e32 v58, v144
	v_mov_b32_e32 v59, v145
	v_mov_b32_e32 v60, v146
	v_mov_b32_e32 v61, v147
	v_lshl_add_u64 v[62:63], v[26:27], 0, s[8:9]
	s_add_u32 s8, s8, 0x800
	s_addc_u32 s9, s9, 0
	v_add_co_u32_e32 v62, vcc, s78, v62
	s_nop 0
	s_nop 0
	v_addc_co_u32_e32 v63, vcc, 0, v63, vcc
	v_pk_mul_f32 v[64:65], v[48:49], v[48:49]
	v_pk_mul_f32 v[66:67], v[46:47], v[46:47]
	v_pk_mul_f32 v[68:69], v[52:53], v[52:53]
	v_pk_mul_f32 v[70:71], v[50:51], v[50:51]
	v_pk_mov_b32 v[76:77], v[66:67], v[64:65] op_sel:[1,0]
	v_mov_b32_e32 v67, v65
	v_pk_mov_b32 v[64:65], v[70:71], v[68:69] op_sel:[1,0]
	v_mov_b32_e32 v71, v69
	v_mul_f32_e32 v75, v58, v58
	v_mul_f32_e32 v72, v55, v55
	v_mul_f32_e32 v74, v57, v57
	v_pk_add_f32 v[66:67], v[76:77], v[66:67]
	v_pk_add_f32 v[64:65], v[64:65], v[70:71]
	v_mul_f32_e32 v78, v59, v59
	v_mul_f32_e32 v79, v60, v60
	v_mul_f32_e32 v80, v61, v61
	v_pk_fma_f32 v[68:69], v[54:55], v[54:55], v[72:73] op_sel_hi:[1,1,0]
	v_pk_fma_f32 v[72:73], v[56:57], v[56:57], v[74:75] op_sel_hi:[1,1,0]
	v_pk_add_f32 v[66:67], v[66:67], v[66:67] op_sel:[0,1] op_sel_hi:[1,0]
	v_pk_add_f32 v[64:65], v[64:65], v[64:65] op_sel:[0,1] op_sel_hi:[1,0]
	v_mov_b32_e32 v69, v79
	v_mov_b32_e32 v73, v80
	v_mov_b32_e32 v67, v75
	v_mov_b32_e32 v65, v78
	v_pk_add_f32 v[68:69], v[68:69], v[72:73]
	v_pk_add_f32 v[64:65], v[66:67], v[64:65]
	s_nop 0
	v_pk_add_f32 v[64:65], v[64:65], v[68:69]
	s_nop 0
	v_add_f32_e32 v64, v64, v65
	s_nop 1
	v_add_f32_dpp v64, v64, v64 quad_perm:[1,0,3,2] row_mask:0xf bank_mask:0xf bound_ctrl:1
	s_nop 1
	v_add_f32_dpp v64, v64, v64 quad_perm:[2,3,0,1] row_mask:0xf bank_mask:0xf bound_ctrl:1
	s_nop 1
	v_add_f32_dpp v64, v64, v64 row_half_mirror row_mask:0xf bank_mask:0xf bound_ctrl:1
	s_nop 1
	v_add_f32_dpp v64, v64, v64 row_mirror row_mask:0xf bank_mask:0xf bound_ctrl:1
	s_nop 0
	v_readlane_b32 s5, v64, 16
	v_readlane_b32 s11, v64, 48
	v_readlane_b32 s12, v64, 0
	v_readlane_b32 s13, v64, 32
	v_mov_b32_e32 v64, s5
	v_mov_b32_e32 v65, s11
	v_pk_add_f32 v[64:65], s[12:13], v[64:65]
	s_nop 0
	v_add_f32_e32 v64, v64, v65
	v_fmamk_f32 v64, v64, 0x3a800000, v212
	v_rsq_f32_e32 v64, v64
	s_nop 0
	v_pk_mul_f32 v[46:47], v[46:47], v[64:65] op_sel_hi:[1,0]
	v_pk_mul_f32 v[48:49], v[48:49], v[64:65] op_sel_hi:[1,0]
	v_pk_mul_f32 v[50:51], v[50:51], v[64:65] op_sel_hi:[1,0]
	v_pk_mul_f32 v[52:53], v[52:53], v[64:65] op_sel_hi:[1,0]
	v_pk_mul_f32 v[54:55], v[54:55], v[64:65] op_sel_hi:[1,0]
	v_pk_mul_f32 v[56:57], v[56:57], v[64:65] op_sel_hi:[1,0]
	v_pk_mul_f32 v[58:59], v[58:59], v[64:65] op_sel_hi:[1,0]
	v_pk_mul_f32 v[60:61], v[60:61], v[64:65] op_sel_hi:[1,0]
	v_pk_fma_f32 v[48:49], v[30:31], v[48:49], v[2:3]
	v_pk_fma_f32 v[46:47], v[32:33], v[46:47], v[0:1]
	v_pk_fma_f32 v[52:53], v[34:35], v[52:53], v[6:7]
	v_pk_fma_f32 v[50:51], v[36:37], v[50:51], v[4:5]
	v_pk_fma_f32 v[56:57], v[38:39], v[56:57], v[10:11]
	v_pk_fma_f32 v[54:55], v[40:41], v[54:55], v[8:9]
	v_pk_fma_f32 v[60:61], v[42:43], v[60:61], v[14:15]
	v_pk_fma_f32 v[58:59], v[44:45], v[58:59], v[12:13]
	v_cvt_pk_bf16_f32 v46, v46, v47
	v_cvt_pk_bf16_f32 v47, v48, v49
	v_cvt_pk_bf16_f32 v48, v50, v51
	v_cvt_pk_bf16_f32 v49, v52, v53
	v_cvt_pk_bf16_f32 v50, v54, v55
	v_cvt_pk_bf16_f32 v51, v56, v57
	v_cvt_pk_bf16_f32 v52, v58, v59
	v_cvt_pk_bf16_f32 v53, v60, v61
	global_store_dwordx2 v[62:63], v[46:47], off
	global_store_dwordx2 v[62:63], v[48:49], off offset:512
	global_store_dwordx2 v[62:63], v[50:51], off offset:1024
	global_store_dwordx2 v[62:63], v[52:53], off offset:1536
	s_waitcnt vmcnt(28)
	s_nop 1
	v_mov_b32_e32 v46, v180
	v_mov_b32_e32 v47, v181
	v_mov_b32_e32 v48, v182
	v_mov_b32_e32 v49, v183
	v_mov_b32_e32 v50, v184
	v_mov_b32_e32 v51, v185
	v_mov_b32_e32 v52, v186
	v_mov_b32_e32 v53, v187
	v_mov_b32_e32 v54, v188
	v_mov_b32_e32 v55, v189
	v_mov_b32_e32 v56, v190
	v_mov_b32_e32 v57, v191
	v_mov_b32_e32 v58, v192
	v_mov_b32_e32 v59, v193
	v_mov_b32_e32 v60, v194
	v_mov_b32_e32 v61, v195
	v_lshl_add_u64 v[62:63], v[26:27], 0, s[8:9]
	s_add_u32 s8, s8, 0x800
	s_addc_u32 s9, s9, 0
	v_add_co_u32_e32 v62, vcc, s78, v62
	s_nop 0
	s_nop 0
	v_addc_co_u32_e32 v63, vcc, 0, v63, vcc
	v_pk_mul_f32 v[64:65], v[48:49], v[48:49]
	v_pk_mul_f32 v[66:67], v[46:47], v[46:47]
	v_pk_mul_f32 v[68:69], v[52:53], v[52:53]
	v_pk_mul_f32 v[70:71], v[50:51], v[50:51]
	v_pk_mov_b32 v[76:77], v[66:67], v[64:65] op_sel:[1,0]
	v_mov_b32_e32 v67, v65
	v_pk_mov_b32 v[64:65], v[70:71], v[68:69] op_sel:[1,0]
	v_mov_b32_e32 v71, v69
	v_mul_f32_e32 v75, v58, v58
	v_mul_f32_e32 v72, v55, v55
	v_mul_f32_e32 v74, v57, v57
	v_pk_add_f32 v[66:67], v[76:77], v[66:67]
	v_pk_add_f32 v[64:65], v[64:65], v[70:71]
	v_mul_f32_e32 v78, v59, v59
	v_mul_f32_e32 v79, v60, v60
	v_mul_f32_e32 v80, v61, v61
	v_pk_fma_f32 v[68:69], v[54:55], v[54:55], v[72:73] op_sel_hi:[1,1,0]
	v_pk_fma_f32 v[72:73], v[56:57], v[56:57], v[74:75] op_sel_hi:[1,1,0]
	v_pk_add_f32 v[66:67], v[66:67], v[66:67] op_sel:[0,1] op_sel_hi:[1,0]
	v_pk_add_f32 v[64:65], v[64:65], v[64:65] op_sel:[0,1] op_sel_hi:[1,0]
	v_mov_b32_e32 v69, v79
	v_mov_b32_e32 v73, v80
	v_mov_b32_e32 v67, v75
	v_mov_b32_e32 v65, v78
	v_pk_add_f32 v[68:69], v[68:69], v[72:73]
	v_pk_add_f32 v[64:65], v[66:67], v[64:65]
	s_nop 0
	v_pk_add_f32 v[64:65], v[64:65], v[68:69]
	s_nop 0
	v_add_f32_e32 v64, v64, v65
	s_nop 1
	v_add_f32_dpp v64, v64, v64 quad_perm:[1,0,3,2] row_mask:0xf bank_mask:0xf bound_ctrl:1
	s_nop 1
	v_add_f32_dpp v64, v64, v64 quad_perm:[2,3,0,1] row_mask:0xf bank_mask:0xf bound_ctrl:1
	s_nop 1
	v_add_f32_dpp v64, v64, v64 row_half_mirror row_mask:0xf bank_mask:0xf bound_ctrl:1
	s_nop 1
	v_add_f32_dpp v64, v64, v64 row_mirror row_mask:0xf bank_mask:0xf bound_ctrl:1
	s_nop 0
	v_readlane_b32 s5, v64, 16
	v_readlane_b32 s11, v64, 48
	v_readlane_b32 s12, v64, 0
	v_readlane_b32 s13, v64, 32
	v_mov_b32_e32 v64, s5
	v_mov_b32_e32 v65, s11
	v_pk_add_f32 v[64:65], s[12:13], v[64:65]
	s_nop 0
	v_add_f32_e32 v64, v64, v65
	v_fmamk_f32 v64, v64, 0x3a800000, v212
	v_rsq_f32_e32 v64, v64
	s_nop 0
	v_pk_mul_f32 v[46:47], v[46:47], v[64:65] op_sel_hi:[1,0]
	v_pk_mul_f32 v[48:49], v[48:49], v[64:65] op_sel_hi:[1,0]
	v_pk_mul_f32 v[50:51], v[50:51], v[64:65] op_sel_hi:[1,0]
	v_pk_mul_f32 v[52:53], v[52:53], v[64:65] op_sel_hi:[1,0]
	v_pk_mul_f32 v[54:55], v[54:55], v[64:65] op_sel_hi:[1,0]
	v_pk_mul_f32 v[56:57], v[56:57], v[64:65] op_sel_hi:[1,0]
	v_pk_mul_f32 v[58:59], v[58:59], v[64:65] op_sel_hi:[1,0]
	v_pk_mul_f32 v[60:61], v[60:61], v[64:65] op_sel_hi:[1,0]
	v_pk_fma_f32 v[48:49], v[30:31], v[48:49], v[2:3]
	v_pk_fma_f32 v[46:47], v[32:33], v[46:47], v[0:1]
	v_pk_fma_f32 v[52:53], v[34:35], v[52:53], v[6:7]
	v_pk_fma_f32 v[50:51], v[36:37], v[50:51], v[4:5]
	v_pk_fma_f32 v[56:57], v[38:39], v[56:57], v[10:11]
	v_pk_fma_f32 v[54:55], v[40:41], v[54:55], v[8:9]
	v_pk_fma_f32 v[60:61], v[42:43], v[60:61], v[14:15]
	v_pk_fma_f32 v[58:59], v[44:45], v[58:59], v[12:13]
	v_cvt_pk_bf16_f32 v46, v46, v47
	v_cvt_pk_bf16_f32 v47, v48, v49
	v_cvt_pk_bf16_f32 v48, v50, v51
	v_cvt_pk_bf16_f32 v49, v52, v53
	v_cvt_pk_bf16_f32 v50, v54, v55
	v_cvt_pk_bf16_f32 v51, v56, v57
	v_cvt_pk_bf16_f32 v52, v58, v59
	v_cvt_pk_bf16_f32 v53, v60, v61
	global_store_dwordx2 v[62:63], v[46:47], off
	global_store_dwordx2 v[62:63], v[48:49], off offset:512
	global_store_dwordx2 v[62:63], v[50:51], off offset:1024
	global_store_dwordx2 v[62:63], v[52:53], off offset:1536
	s_waitcnt vmcnt(28)
	s_nop 1
	v_mov_b32_e32 v46, v196
	v_mov_b32_e32 v47, v197
	v_mov_b32_e32 v48, v198
	v_mov_b32_e32 v49, v199
	v_mov_b32_e32 v50, v200
	v_mov_b32_e32 v51, v201
	v_mov_b32_e32 v52, v202
	v_mov_b32_e32 v53, v203
	v_mov_b32_e32 v54, v204
	v_mov_b32_e32 v55, v205
	v_mov_b32_e32 v56, v206
	v_mov_b32_e32 v57, v207
	v_mov_b32_e32 v58, v208
	v_mov_b32_e32 v59, v209
	v_mov_b32_e32 v60, v210
	v_mov_b32_e32 v61, v211
	v_lshl_add_u64 v[62:63], v[26:27], 0, s[8:9]
	s_add_u32 s8, s8, 0x800
	s_addc_u32 s9, s9, 0
	v_add_co_u32_e32 v62, vcc, s78, v62
	s_nop 0
	s_nop 0
	v_addc_co_u32_e32 v63, vcc, 0, v63, vcc
	v_pk_mul_f32 v[64:65], v[48:49], v[48:49]
	v_pk_mul_f32 v[66:67], v[46:47], v[46:47]
	v_pk_mul_f32 v[68:69], v[52:53], v[52:53]
	v_pk_mul_f32 v[70:71], v[50:51], v[50:51]
	v_pk_mov_b32 v[76:77], v[66:67], v[64:65] op_sel:[1,0]
	v_mov_b32_e32 v67, v65
	v_pk_mov_b32 v[64:65], v[70:71], v[68:69] op_sel:[1,0]
	v_mov_b32_e32 v71, v69
	v_mul_f32_e32 v75, v58, v58
	v_mul_f32_e32 v72, v55, v55
	v_mul_f32_e32 v74, v57, v57
	v_pk_add_f32 v[66:67], v[76:77], v[66:67]
	v_pk_add_f32 v[64:65], v[64:65], v[70:71]
	v_mul_f32_e32 v78, v59, v59
	v_mul_f32_e32 v79, v60, v60
	v_mul_f32_e32 v80, v61, v61
	v_pk_fma_f32 v[68:69], v[54:55], v[54:55], v[72:73] op_sel_hi:[1,1,0]
	v_pk_fma_f32 v[72:73], v[56:57], v[56:57], v[74:75] op_sel_hi:[1,1,0]
	v_pk_add_f32 v[66:67], v[66:67], v[66:67] op_sel:[0,1] op_sel_hi:[1,0]
	v_pk_add_f32 v[64:65], v[64:65], v[64:65] op_sel:[0,1] op_sel_hi:[1,0]
	v_mov_b32_e32 v69, v79
	v_mov_b32_e32 v73, v80
	v_mov_b32_e32 v67, v75
	v_mov_b32_e32 v65, v78
	v_pk_add_f32 v[68:69], v[68:69], v[72:73]
	v_pk_add_f32 v[64:65], v[66:67], v[64:65]
	s_nop 0
	v_pk_add_f32 v[64:65], v[64:65], v[68:69]
	s_nop 0
	v_add_f32_e32 v64, v64, v65
	s_nop 1
	v_add_f32_dpp v64, v64, v64 quad_perm:[1,0,3,2] row_mask:0xf bank_mask:0xf bound_ctrl:1
	s_nop 1
	v_add_f32_dpp v64, v64, v64 quad_perm:[2,3,0,1] row_mask:0xf bank_mask:0xf bound_ctrl:1
	s_nop 1
	v_add_f32_dpp v64, v64, v64 row_half_mirror row_mask:0xf bank_mask:0xf bound_ctrl:1
	s_nop 1
	v_add_f32_dpp v64, v64, v64 row_mirror row_mask:0xf bank_mask:0xf bound_ctrl:1
	s_nop 0
	v_readlane_b32 s5, v64, 16
	v_readlane_b32 s11, v64, 48
	v_readlane_b32 s12, v64, 0
	v_readlane_b32 s13, v64, 32
	v_mov_b32_e32 v64, s5
	v_mov_b32_e32 v65, s11
	v_pk_add_f32 v[64:65], s[12:13], v[64:65]
	s_nop 0
	v_add_f32_e32 v64, v64, v65
	v_fmamk_f32 v64, v64, 0x3a800000, v212
	v_rsq_f32_e32 v64, v64
	s_nop 0
	v_pk_mul_f32 v[46:47], v[46:47], v[64:65] op_sel_hi:[1,0]
	v_pk_mul_f32 v[48:49], v[48:49], v[64:65] op_sel_hi:[1,0]
	v_pk_mul_f32 v[50:51], v[50:51], v[64:65] op_sel_hi:[1,0]
	v_pk_mul_f32 v[52:53], v[52:53], v[64:65] op_sel_hi:[1,0]
	v_pk_mul_f32 v[54:55], v[54:55], v[64:65] op_sel_hi:[1,0]
	v_pk_mul_f32 v[56:57], v[56:57], v[64:65] op_sel_hi:[1,0]
	v_pk_mul_f32 v[58:59], v[58:59], v[64:65] op_sel_hi:[1,0]
	v_pk_mul_f32 v[60:61], v[60:61], v[64:65] op_sel_hi:[1,0]
	v_pk_fma_f32 v[48:49], v[30:31], v[48:49], v[2:3]
	v_pk_fma_f32 v[46:47], v[32:33], v[46:47], v[0:1]
	v_pk_fma_f32 v[52:53], v[34:35], v[52:53], v[6:7]
	v_pk_fma_f32 v[50:51], v[36:37], v[50:51], v[4:5]
	v_pk_fma_f32 v[56:57], v[38:39], v[56:57], v[10:11]
	v_pk_fma_f32 v[54:55], v[40:41], v[54:55], v[8:9]
	v_pk_fma_f32 v[60:61], v[42:43], v[60:61], v[14:15]
	v_pk_fma_f32 v[58:59], v[44:45], v[58:59], v[12:13]
	v_cvt_pk_bf16_f32 v46, v46, v47
	v_cvt_pk_bf16_f32 v47, v48, v49
	v_cvt_pk_bf16_f32 v48, v50, v51
	v_cvt_pk_bf16_f32 v49, v52, v53
	v_cvt_pk_bf16_f32 v50, v54, v55
	v_cvt_pk_bf16_f32 v51, v56, v57
	v_cvt_pk_bf16_f32 v52, v58, v59
	v_cvt_pk_bf16_f32 v53, v60, v61
	global_store_dwordx2 v[62:63], v[46:47], off
	global_store_dwordx2 v[62:63], v[48:49], off offset:512
	global_store_dwordx2 v[62:63], v[50:51], off offset:1024
	global_store_dwordx2 v[62:63], v[52:53], off offset:1536
	s_waitcnt vmcnt(28)
	s_nop 1
	v_mov_b32_e32 v46, v226
	v_mov_b32_e32 v47, v227
	v_mov_b32_e32 v48, v228
	v_mov_b32_e32 v49, v229
	v_mov_b32_e32 v50, v230
	v_mov_b32_e32 v51, v231
	v_mov_b32_e32 v52, v232
	v_mov_b32_e32 v53, v233
	v_mov_b32_e32 v54, v234
	v_mov_b32_e32 v55, v235
	v_mov_b32_e32 v56, v236
	v_mov_b32_e32 v57, v237
	v_mov_b32_e32 v58, v238
	v_mov_b32_e32 v59, v239
	v_mov_b32_e32 v60, v240
	v_mov_b32_e32 v61, v241
	v_lshl_add_u64 v[62:63], v[26:27], 0, s[8:9]
	s_add_u32 s8, s8, 0x800
	s_addc_u32 s9, s9, 0
	v_add_co_u32_e32 v62, vcc, s78, v62
	s_nop 0
	s_nop 0
	v_addc_co_u32_e32 v63, vcc, 0, v63, vcc
	v_pk_mul_f32 v[64:65], v[48:49], v[48:49]
	v_pk_mul_f32 v[66:67], v[46:47], v[46:47]
	v_pk_mul_f32 v[68:69], v[52:53], v[52:53]
	v_pk_mul_f32 v[70:71], v[50:51], v[50:51]
	v_pk_mov_b32 v[76:77], v[66:67], v[64:65] op_sel:[1,0]
	v_mov_b32_e32 v67, v65
	v_pk_mov_b32 v[64:65], v[70:71], v[68:69] op_sel:[1,0]
	v_mov_b32_e32 v71, v69
	v_mul_f32_e32 v75, v58, v58
	v_mul_f32_e32 v72, v55, v55
	v_mul_f32_e32 v74, v57, v57
	v_pk_add_f32 v[66:67], v[76:77], v[66:67]
	v_pk_add_f32 v[64:65], v[64:65], v[70:71]
	v_mul_f32_e32 v78, v59, v59
	v_mul_f32_e32 v79, v60, v60
	v_mul_f32_e32 v80, v61, v61
	v_pk_fma_f32 v[68:69], v[54:55], v[54:55], v[72:73] op_sel_hi:[1,1,0]
	v_pk_fma_f32 v[72:73], v[56:57], v[56:57], v[74:75] op_sel_hi:[1,1,0]
	v_pk_add_f32 v[66:67], v[66:67], v[66:67] op_sel:[0,1] op_sel_hi:[1,0]
	v_pk_add_f32 v[64:65], v[64:65], v[64:65] op_sel:[0,1] op_sel_hi:[1,0]
	v_mov_b32_e32 v69, v79
	v_mov_b32_e32 v73, v80
	v_mov_b32_e32 v67, v75
	v_mov_b32_e32 v65, v78
	v_pk_add_f32 v[68:69], v[68:69], v[72:73]
	v_pk_add_f32 v[64:65], v[66:67], v[64:65]
	s_nop 0
	v_pk_add_f32 v[64:65], v[64:65], v[68:69]
	s_nop 0
	v_add_f32_e32 v64, v64, v65
	s_nop 1
	v_add_f32_dpp v64, v64, v64 quad_perm:[1,0,3,2] row_mask:0xf bank_mask:0xf bound_ctrl:1
	s_nop 1
	v_add_f32_dpp v64, v64, v64 quad_perm:[2,3,0,1] row_mask:0xf bank_mask:0xf bound_ctrl:1
	s_nop 1
	v_add_f32_dpp v64, v64, v64 row_half_mirror row_mask:0xf bank_mask:0xf bound_ctrl:1
	s_nop 1
	v_add_f32_dpp v64, v64, v64 row_mirror row_mask:0xf bank_mask:0xf bound_ctrl:1
	s_nop 0
	v_readlane_b32 s5, v64, 16
	v_readlane_b32 s11, v64, 48
	v_readlane_b32 s12, v64, 0
	v_readlane_b32 s13, v64, 32
	v_mov_b32_e32 v64, s5
	v_mov_b32_e32 v65, s11
	v_pk_add_f32 v[64:65], s[12:13], v[64:65]
	s_nop 0
	v_add_f32_e32 v64, v64, v65
	v_fmamk_f32 v64, v64, 0x3a800000, v212
	v_rsq_f32_e32 v64, v64
	s_nop 0
	v_pk_mul_f32 v[46:47], v[46:47], v[64:65] op_sel_hi:[1,0]
	v_pk_mul_f32 v[48:49], v[48:49], v[64:65] op_sel_hi:[1,0]
	v_pk_mul_f32 v[50:51], v[50:51], v[64:65] op_sel_hi:[1,0]
	v_pk_mul_f32 v[52:53], v[52:53], v[64:65] op_sel_hi:[1,0]
	v_pk_mul_f32 v[54:55], v[54:55], v[64:65] op_sel_hi:[1,0]
	v_pk_mul_f32 v[56:57], v[56:57], v[64:65] op_sel_hi:[1,0]
	v_pk_mul_f32 v[58:59], v[58:59], v[64:65] op_sel_hi:[1,0]
	v_pk_mul_f32 v[60:61], v[60:61], v[64:65] op_sel_hi:[1,0]
	v_pk_fma_f32 v[48:49], v[30:31], v[48:49], v[2:3]
	v_pk_fma_f32 v[46:47], v[32:33], v[46:47], v[0:1]
	v_pk_fma_f32 v[52:53], v[34:35], v[52:53], v[6:7]
	v_pk_fma_f32 v[50:51], v[36:37], v[50:51], v[4:5]
	v_pk_fma_f32 v[56:57], v[38:39], v[56:57], v[10:11]
	v_pk_fma_f32 v[54:55], v[40:41], v[54:55], v[8:9]
	v_pk_fma_f32 v[60:61], v[42:43], v[60:61], v[14:15]
	v_pk_fma_f32 v[58:59], v[44:45], v[58:59], v[12:13]
	v_cvt_pk_bf16_f32 v46, v46, v47
	v_cvt_pk_bf16_f32 v47, v48, v49
	v_cvt_pk_bf16_f32 v48, v50, v51
	v_cvt_pk_bf16_f32 v49, v52, v53
	v_cvt_pk_bf16_f32 v50, v54, v55
	v_cvt_pk_bf16_f32 v51, v56, v57
	v_cvt_pk_bf16_f32 v52, v58, v59
	v_cvt_pk_bf16_f32 v53, v60, v61
	global_store_dwordx2 v[62:63], v[46:47], off
	global_store_dwordx2 v[62:63], v[48:49], off offset:512
	global_store_dwordx2 v[62:63], v[50:51], off offset:1024
	global_store_dwordx2 v[62:63], v[52:53], off offset:1536
	s_waitcnt vmcnt(28)
	s_nop 1
	v_mov_b32_e32 v46, v84
	v_mov_b32_e32 v47, v85
	v_mov_b32_e32 v48, v86
	v_mov_b32_e32 v49, v87
	v_mov_b32_e32 v50, v88
	v_mov_b32_e32 v51, v89
	v_mov_b32_e32 v52, v90
	v_mov_b32_e32 v53, v91
	v_mov_b32_e32 v54, v92
	v_mov_b32_e32 v55, v93
	v_mov_b32_e32 v56, v94
	v_mov_b32_e32 v57, v95
	v_mov_b32_e32 v58, v96
	v_mov_b32_e32 v59, v97
	v_mov_b32_e32 v60, v98
	v_mov_b32_e32 v61, v99
	v_lshl_add_u64 v[62:63], v[26:27], 0, s[8:9]
	s_add_u32 s8, s8, 0x800
	s_addc_u32 s9, s9, 0
	v_add_co_u32_e32 v62, vcc, s78, v62
	s_nop 0
	s_nop 0
	v_addc_co_u32_e32 v63, vcc, 0, v63, vcc
	v_pk_mul_f32 v[64:65], v[48:49], v[48:49]
	v_pk_mul_f32 v[66:67], v[46:47], v[46:47]
	v_pk_mul_f32 v[68:69], v[52:53], v[52:53]
	v_pk_mul_f32 v[70:71], v[50:51], v[50:51]
	v_pk_mov_b32 v[76:77], v[66:67], v[64:65] op_sel:[1,0]
	v_mov_b32_e32 v67, v65
	v_pk_mov_b32 v[64:65], v[70:71], v[68:69] op_sel:[1,0]
	v_mov_b32_e32 v71, v69
	v_mul_f32_e32 v75, v58, v58
	v_mul_f32_e32 v72, v55, v55
	v_mul_f32_e32 v74, v57, v57
	v_pk_add_f32 v[66:67], v[76:77], v[66:67]
	v_pk_add_f32 v[64:65], v[64:65], v[70:71]
	v_mul_f32_e32 v78, v59, v59
	v_mul_f32_e32 v79, v60, v60
	v_mul_f32_e32 v80, v61, v61
	v_pk_fma_f32 v[68:69], v[54:55], v[54:55], v[72:73] op_sel_hi:[1,1,0]
	v_pk_fma_f32 v[72:73], v[56:57], v[56:57], v[74:75] op_sel_hi:[1,1,0]
	v_pk_add_f32 v[66:67], v[66:67], v[66:67] op_sel:[0,1] op_sel_hi:[1,0]
	v_pk_add_f32 v[64:65], v[64:65], v[64:65] op_sel:[0,1] op_sel_hi:[1,0]
	v_mov_b32_e32 v69, v79
	v_mov_b32_e32 v73, v80
	v_mov_b32_e32 v67, v75
	v_mov_b32_e32 v65, v78
	v_pk_add_f32 v[68:69], v[68:69], v[72:73]
	v_pk_add_f32 v[64:65], v[66:67], v[64:65]
	s_nop 0
	v_pk_add_f32 v[64:65], v[64:65], v[68:69]
	s_nop 0
	v_add_f32_e32 v64, v64, v65
	s_nop 1
	v_add_f32_dpp v64, v64, v64 quad_perm:[1,0,3,2] row_mask:0xf bank_mask:0xf bound_ctrl:1
	s_nop 1
	v_add_f32_dpp v64, v64, v64 quad_perm:[2,3,0,1] row_mask:0xf bank_mask:0xf bound_ctrl:1
	s_nop 1
	v_add_f32_dpp v64, v64, v64 row_half_mirror row_mask:0xf bank_mask:0xf bound_ctrl:1
	s_nop 1
	v_add_f32_dpp v64, v64, v64 row_mirror row_mask:0xf bank_mask:0xf bound_ctrl:1
	s_nop 0
	v_readlane_b32 s5, v64, 16
	v_readlane_b32 s11, v64, 48
	v_readlane_b32 s12, v64, 0
	v_readlane_b32 s13, v64, 32
	v_mov_b32_e32 v64, s5
	v_mov_b32_e32 v65, s11
	v_pk_add_f32 v[64:65], s[12:13], v[64:65]
	s_nop 0
	v_add_f32_e32 v64, v64, v65
	v_fmamk_f32 v64, v64, 0x3a800000, v212
	v_rsq_f32_e32 v64, v64
	s_nop 0
	v_pk_mul_f32 v[46:47], v[46:47], v[64:65] op_sel_hi:[1,0]
	v_pk_mul_f32 v[48:49], v[48:49], v[64:65] op_sel_hi:[1,0]
	v_pk_mul_f32 v[50:51], v[50:51], v[64:65] op_sel_hi:[1,0]
	v_pk_mul_f32 v[52:53], v[52:53], v[64:65] op_sel_hi:[1,0]
	v_pk_mul_f32 v[54:55], v[54:55], v[64:65] op_sel_hi:[1,0]
	v_pk_mul_f32 v[56:57], v[56:57], v[64:65] op_sel_hi:[1,0]
	v_pk_mul_f32 v[58:59], v[58:59], v[64:65] op_sel_hi:[1,0]
	v_pk_mul_f32 v[60:61], v[60:61], v[64:65] op_sel_hi:[1,0]
	v_pk_fma_f32 v[48:49], v[30:31], v[48:49], v[2:3]
	v_pk_fma_f32 v[46:47], v[32:33], v[46:47], v[0:1]
	v_pk_fma_f32 v[52:53], v[34:35], v[52:53], v[6:7]
	v_pk_fma_f32 v[50:51], v[36:37], v[50:51], v[4:5]
	v_pk_fma_f32 v[56:57], v[38:39], v[56:57], v[10:11]
	v_pk_fma_f32 v[54:55], v[40:41], v[54:55], v[8:9]
	v_pk_fma_f32 v[60:61], v[42:43], v[60:61], v[14:15]
	v_pk_fma_f32 v[58:59], v[44:45], v[58:59], v[12:13]
	v_cvt_pk_bf16_f32 v46, v46, v47
	v_cvt_pk_bf16_f32 v47, v48, v49
	v_cvt_pk_bf16_f32 v48, v50, v51
	v_cvt_pk_bf16_f32 v49, v52, v53
	v_cvt_pk_bf16_f32 v50, v54, v55
	v_cvt_pk_bf16_f32 v51, v56, v57
	v_cvt_pk_bf16_f32 v52, v58, v59
	v_cvt_pk_bf16_f32 v53, v60, v61
	global_store_dwordx2 v[62:63], v[46:47], off
	global_store_dwordx2 v[62:63], v[48:49], off offset:512
	global_store_dwordx2 v[62:63], v[50:51], off offset:1024
	global_store_dwordx2 v[62:63], v[52:53], off offset:1536
	s_add_i32 s10, s10, s38
	s_add_i32 s4, s4, s14
	s_cmpk_gt_i32 s10, 0x7ff
	s_cbranch_scc0 .LBB0_80
	v_readlane_b32 s88, v253, 19
	v_readlane_b32 s50, v253, 21
	v_readlane_b32 s48, v253, 23
	v_readlane_b32 s52, v253, 25
	v_readlane_b32 s89, v253, 20
	v_readlane_b32 s51, v253, 22
	v_readlane_b32 s49, v253, 24
	v_readlane_b32 s53, v253, 26
	s_mov_b32 s80, 0x13000
	v_readlane_b32 s62, v253, 27
